# scan loop: the s_nop wait state in front of the operand exchange replaced by reordering the copies and placing the prefetch-offset scalar pair between the two exchanges
# baseline (speedup 1.0000x reference)
.Lscan_go_0:
	v_mfma_f32_32x32x16_bf16 v[0:15], v[120:123], v[104:107], 0
	s_addk_i32 s16, 0x800
	v_mfma_f32_32x32x16_bf16 v[16:31], v[120:123], v[116:119], 0
	v_mfma_f32_32x32x16_bf16 v[32:47], v[120:123], v[92:95], 0
	v_mfma_f32_32x32x16_bf16 v[196:211], v[120:123], v[112:115], 0
	v_mov_b32_e32 v218, v120
	v_mov_b32_e32 v220, v122
	v_mov_b32_e32 v219, v121
	v_mov_b32_e32 v221, v123
	v_permlane32_swap_b32_e32 v218, v220
	s_add_u32 s0, s0, 0x40000
	s_addc_u32 s1, s1, 0
	v_permlane32_swap_b32_e32 v219, v221
	v_lshl_add_u64 v[216:217], v[152:153], 0, s[0:1]
	global_load_dwordx4 v[120:123], v[216:217], off
	v_lshlrev_b32_e32 v228, 16, v218
	v_and_b32_e32 v229, 0xffff0000, v218
	v_lshlrev_b32_e32 v230, 16, v219
	v_and_b32_e32 v231, 0xffff0000, v219
	v_lshlrev_b32_e32 v232, 16, v220
	v_and_b32_e32 v233, 0xffff0000, v220
	v_lshlrev_b32_e32 v251, 16, v221
	v_and_b32_e32 v252, 0xffff0000, v221
	v_permlane32_swap_b32_e32 v0, v16
	v_permlane32_swap_b32_e32 v1, v17
	v_permlane32_swap_b32_e32 v2, v18
	v_permlane32_swap_b32_e32 v3, v19
	v_permlane32_swap_b32_e32 v4, v20
	v_permlane32_swap_b32_e32 v5, v21
	v_permlane32_swap_b32_e32 v6, v22
	v_permlane32_swap_b32_e32 v7, v23
	v_permlane32_swap_b32_e32 v8, v24
	v_permlane32_swap_b32_e32 v9, v25
	v_permlane32_swap_b32_e32 v10, v26
	v_permlane32_swap_b32_e32 v11, v27
	v_permlane32_swap_b32_e32 v12, v28
	v_permlane32_swap_b32_e32 v13, v29
	v_permlane32_swap_b32_e32 v14, v30
	v_permlane32_swap_b32_e32 v15, v31
	v_permlane32_swap_b32_e32 v32, v196
	v_permlane32_swap_b32_e32 v33, v197
	v_permlane32_swap_b32_e32 v34, v198
	v_permlane32_swap_b32_e32 v35, v199
	v_permlane32_swap_b32_e32 v36, v200
	v_permlane32_swap_b32_e32 v37, v201
	v_permlane32_swap_b32_e32 v38, v202
	v_permlane32_swap_b32_e32 v39, v203
	v_permlane32_swap_b32_e32 v40, v204
	v_permlane32_swap_b32_e32 v41, v205
	v_permlane32_swap_b32_e32 v42, v206
	v_permlane32_swap_b32_e32 v43, v207
	v_permlane32_swap_b32_e32 v44, v208
	v_permlane32_swap_b32_e32 v45, v209
	v_permlane32_swap_b32_e32 v46, v210
	v_permlane32_swap_b32_e32 v47, v211
	v_fmac_f32_e32 v0, v160, v188
	v_fmac_f32_e32 v32, v160, v189
	v_fma_f32 v0, -v161, v189, v0
	v_fmac_f32_e32 v32, v161, v188
	v_fmac_f32_e32 v1, v160, v0
	v_fmac_f32_e32 v33, v160, v32
	v_cvt_pk_bf16_f32 v212, v0, v32
	v_fma_f32 v1, -v161, v32, v1
	v_fmac_f32_e32 v33, v161, v0
	v_fmac_f32_e32 v2, v160, v1
	v_fmac_f32_e32 v34, v160, v33
	v_cvt_pk_bf16_f32 v213, v1, v33
	v_fma_f32 v2, -v161, v33, v2
	v_fmac_f32_e32 v34, v161, v1
	ds_write2_b32 v222, v212, v213 offset0:0 offset1:68
	v_fmac_f32_e32 v3, v160, v2
	v_fmac_f32_e32 v35, v160, v34
	v_cvt_pk_bf16_f32 v214, v2, v34
	v_fma_f32 v3, -v161, v34, v3
	v_fmac_f32_e32 v35, v161, v2
	v_fmac_f32_e32 v16, v160, v3
	v_fmac_f32_e32 v196, v160, v35
	v_cvt_pk_bf16_f32 v215, v3, v35
	v_fma_f32 v16, -v161, v35, v16
	v_fmac_f32_e32 v196, v161, v3
	ds_write2_b32 v222, v214, v215 offset0:136 offset1:204
	v_fmac_f32_e32 v17, v160, v16
	v_fmac_f32_e32 v197, v160, v196
	v_cvt_pk_bf16_f32 v212, v16, v196
	v_fma_f32 v17, -v161, v196, v17
	v_fmac_f32_e32 v197, v161, v16
	v_fmac_f32_e32 v18, v160, v17
	v_fmac_f32_e32 v198, v160, v197
	v_cvt_pk_bf16_f32 v213, v17, v197
	v_fma_f32 v18, -v161, v197, v18
	v_fmac_f32_e32 v198, v161, v17
	ds_write2_b32 v223, v212, v213 offset0:0 offset1:68
	v_fmac_f32_e32 v19, v160, v18
	v_fmac_f32_e32 v199, v160, v198
	v_cvt_pk_bf16_f32 v214, v18, v198
	v_fma_f32 v19, -v161, v198, v19
	v_fmac_f32_e32 v199, v161, v18
	v_fmac_f32_e32 v4, v160, v19
	v_fmac_f32_e32 v36, v160, v199
	v_cvt_pk_bf16_f32 v215, v19, v199
	v_fma_f32 v4, -v161, v199, v4
	v_fmac_f32_e32 v36, v161, v19
	ds_write2_b32 v223, v214, v215 offset0:136 offset1:204
	v_fmac_f32_e32 v5, v160, v4
	v_fmac_f32_e32 v37, v160, v36
	v_cvt_pk_bf16_f32 v212, v4, v36
	v_fma_f32 v5, -v161, v36, v5
	v_fmac_f32_e32 v37, v161, v4
	v_fmac_f32_e32 v6, v160, v5
	v_fmac_f32_e32 v38, v160, v37
	v_cvt_pk_bf16_f32 v213, v5, v37
	v_fma_f32 v6, -v161, v37, v6
	v_fmac_f32_e32 v38, v161, v5
	ds_write2_b32 v224, v212, v213 offset0:0 offset1:68
	v_fmac_f32_e32 v7, v160, v6
	v_fmac_f32_e32 v39, v160, v38
	v_cvt_pk_bf16_f32 v214, v6, v38
	v_fma_f32 v7, -v161, v38, v7
	v_fmac_f32_e32 v39, v161, v6
	v_fmac_f32_e32 v20, v160, v7
	v_fmac_f32_e32 v200, v160, v39
	v_cvt_pk_bf16_f32 v215, v7, v39
	v_fma_f32 v20, -v161, v39, v20
	v_fmac_f32_e32 v200, v161, v7
	ds_write2_b32 v224, v214, v215 offset0:136 offset1:204
	v_fmac_f32_e32 v21, v160, v20
	v_fmac_f32_e32 v201, v160, v200
	v_cvt_pk_bf16_f32 v212, v20, v200
	v_fma_f32 v21, -v161, v200, v21
	v_fmac_f32_e32 v201, v161, v20
	v_fmac_f32_e32 v22, v160, v21
	v_fmac_f32_e32 v202, v160, v201
	v_cvt_pk_bf16_f32 v213, v21, v201
	v_fma_f32 v22, -v161, v201, v22
	v_fmac_f32_e32 v202, v161, v21
	ds_write2_b32 v225, v212, v213 offset0:0 offset1:68
	v_fmac_f32_e32 v23, v160, v22
	v_fmac_f32_e32 v203, v160, v202
	v_cvt_pk_bf16_f32 v214, v22, v202
	v_fma_f32 v23, -v161, v202, v23
	v_fmac_f32_e32 v203, v161, v22
	v_fmac_f32_e32 v8, v160, v23
	v_fmac_f32_e32 v40, v160, v203
	v_cvt_pk_bf16_f32 v215, v23, v203
	v_fma_f32 v8, -v161, v203, v8
	v_fmac_f32_e32 v40, v161, v23
	ds_write2_b32 v225, v214, v215 offset0:136 offset1:204
	v_fmac_f32_e32 v9, v160, v8
	v_fmac_f32_e32 v41, v160, v40
	v_cvt_pk_bf16_f32 v212, v8, v40
	v_fma_f32 v9, -v161, v40, v9
	v_fmac_f32_e32 v41, v161, v8
	v_fmac_f32_e32 v10, v160, v9
	v_fmac_f32_e32 v42, v160, v41
	v_cvt_pk_bf16_f32 v213, v9, v41
	v_fma_f32 v10, -v161, v41, v10
	v_fmac_f32_e32 v42, v161, v9
	ds_write2_b32 v226, v212, v213 offset0:0 offset1:68
	v_fmac_f32_e32 v11, v160, v10
	v_fmac_f32_e32 v43, v160, v42
	v_cvt_pk_bf16_f32 v214, v10, v42
	v_fma_f32 v11, -v161, v42, v11
	v_fmac_f32_e32 v43, v161, v10
	v_fmac_f32_e32 v24, v160, v11
	v_fmac_f32_e32 v204, v160, v43
	v_cvt_pk_bf16_f32 v215, v11, v43
	v_fma_f32 v24, -v161, v43, v24
	v_fmac_f32_e32 v204, v161, v11
	ds_write2_b32 v226, v214, v215 offset0:136 offset1:204
	v_fmac_f32_e32 v25, v160, v24
	v_fmac_f32_e32 v205, v160, v204
	v_cvt_pk_bf16_f32 v212, v24, v204
	v_fma_f32 v25, -v161, v204, v25
	v_fmac_f32_e32 v205, v161, v24
	v_fmac_f32_e32 v26, v160, v25
	v_fmac_f32_e32 v206, v160, v205
	v_cvt_pk_bf16_f32 v213, v25, v205
	v_fma_f32 v26, -v161, v205, v26
	v_fmac_f32_e32 v206, v161, v25
	ds_write2_b32 v227, v212, v213 offset0:0 offset1:68
	v_fmac_f32_e32 v27, v160, v26
	v_fmac_f32_e32 v207, v160, v206
	v_cvt_pk_bf16_f32 v214, v26, v206
	v_fma_f32 v27, -v161, v206, v27
	v_fmac_f32_e32 v207, v161, v26
	v_fmac_f32_e32 v12, v160, v27
	v_fmac_f32_e32 v44, v160, v207
	v_cvt_pk_bf16_f32 v215, v27, v207
	v_fma_f32 v12, -v161, v207, v12
	v_fmac_f32_e32 v44, v161, v27
	ds_write2_b32 v227, v214, v215 offset0:136 offset1:204
	v_fmac_f32_e32 v13, v160, v12
	v_fmac_f32_e32 v45, v160, v44
	v_cvt_pk_bf16_f32 v212, v12, v44
	v_fma_f32 v13, -v161, v44, v13
	v_fmac_f32_e32 v45, v161, v12
	v_fmac_f32_e32 v14, v160, v13
	v_fmac_f32_e32 v46, v160, v45
	v_cvt_pk_bf16_f32 v213, v13, v45
	v_fma_f32 v14, -v161, v45, v14
	v_fmac_f32_e32 v46, v161, v13
	ds_write2_b32 v190, v212, v213 offset0:0 offset1:68
	v_fmac_f32_e32 v15, v160, v14
	v_fmac_f32_e32 v47, v160, v46
	v_cvt_pk_bf16_f32 v214, v14, v46
	v_fma_f32 v15, -v161, v46, v15
	v_fmac_f32_e32 v47, v161, v14
	v_fmac_f32_e32 v28, v160, v15
	v_fmac_f32_e32 v208, v160, v47
	v_cvt_pk_bf16_f32 v215, v15, v47
	v_fma_f32 v28, -v161, v47, v28
	v_fmac_f32_e32 v208, v161, v15
	ds_write2_b32 v190, v214, v215 offset0:136 offset1:204
	v_fmac_f32_e32 v29, v160, v28
	v_fmac_f32_e32 v209, v160, v208
	v_cvt_pk_bf16_f32 v212, v28, v208
	v_fma_f32 v29, -v161, v208, v29
	v_fmac_f32_e32 v209, v161, v28
	v_fmac_f32_e32 v30, v160, v29
	v_fmac_f32_e32 v210, v160, v209
	v_cvt_pk_bf16_f32 v213, v29, v209
	v_fma_f32 v30, -v161, v209, v30
	v_fmac_f32_e32 v210, v161, v29
	ds_write2_b32 v191, v212, v213 offset0:0 offset1:68
	v_fmac_f32_e32 v31, v160, v30
	v_fmac_f32_e32 v211, v160, v210
	v_cvt_pk_bf16_f32 v214, v30, v210
	v_fma_f32 v31, -v161, v210, v31
	v_fmac_f32_e32 v211, v161, v30
	v_mov_b32_e32 v188, v31
	v_mov_b32_e32 v189, v211
	v_cvt_pk_bf16_f32 v215, v31, v211
	ds_write2_b32 v191, v214, v215 offset0:136 offset1:204
	s_waitcnt lgkmcnt(0)
	ds_read_b128 v[32:35], v186 offset:18432
	ds_read_b128 v[36:39], v186 offset:18464
	ds_read_b128 v[40:43], v186 offset:18496
	ds_read_b128 v[44:47], v186 offset:18528
	ds_read_b128 v[196:199], v186 offset:18560
	ds_read_b128 v[200:203], v186 offset:18592
	ds_read_b128 v[204:207], v186 offset:18624
	ds_read_b128 v[208:211], v186 offset:18656
	s_waitcnt lgkmcnt(7)
	v_mfma_f32_32x32x16_bf16 v[48:63], v[64:67], v[32:35], 0
	v_fmac_f32_e32 v234, v100, v162
	v_fmac_f32_e32 v235, v101, v163
	v_fmac_f32_e32 v236, v102, v164
	v_fmac_f32_e32 v237, v103, v165
	v_fmac_f32_e32 v238, v80, v166
	v_fmac_f32_e32 v239, v81, v167
	v_fmac_f32_e32 v240, v82, v192
	v_fmac_f32_e32 v241, v83, v193
	v_mul_f32_e32 v242, v234, v234
	s_waitcnt lgkmcnt(6)
	v_mfma_f32_32x32x16_bf16 v[48:63], v[68:71], v[36:39], v[48:63]
	v_mul_f32_e32 v243, v235, v235
	v_mul_f32_e32 v244, v236, v236
	v_mul_f32_e32 v245, v237, v237
	v_mul_f32_e32 v246, v238, v238
	v_mul_f32_e32 v247, v239, v239
	v_mul_f32_e32 v248, v240, v240
	v_mul_f32_e32 v249, v241, v241
	v_fmaak_f32 v242, v242, v184, 0xc0135761
	v_fmaak_f32 v243, v243, v184, 0xc0135761
	s_waitcnt lgkmcnt(5)
	v_mfma_f32_32x32x16_bf16 v[48:63], v[72:75], v[40:43], v[48:63]
	v_fmaak_f32 v244, v244, v184, 0xc0135761
	v_fmaak_f32 v245, v245, v184, 0xc0135761
	v_fmaak_f32 v246, v246, v184, 0xc0135761
	v_fmaak_f32 v247, v247, v184, 0xc0135761
	v_fmaak_f32 v248, v248, v184, 0xc0135761
	v_fmaak_f32 v249, v249, v184, 0xc0135761
	v_mul_f32_e32 v242, v234, v242
	v_mul_f32_e32 v243, v235, v243
	v_mul_f32_e32 v244, v236, v244
	s_waitcnt lgkmcnt(4)
	v_mfma_f32_32x32x16_bf16 v[48:63], v[76:79], v[44:47], v[48:63]
	v_mul_f32_e32 v245, v237, v245
	v_mul_f32_e32 v246, v238, v246
	v_mul_f32_e32 v247, v239, v247
	v_mul_f32_e32 v248, v240, v248
	v_mul_f32_e32 v249, v241, v249
	v_exp_f32_e32 v242, v242
	v_exp_f32_e32 v243, v243
	v_exp_f32_e32 v244, v244
	v_exp_f32_e32 v245, v245
	s_waitcnt lgkmcnt(3)
	v_mfma_f32_32x32x16_bf16 v[48:63], v[84:87], v[196:199], v[48:63]
	v_exp_f32_e32 v246, v246
	v_exp_f32_e32 v247, v247
	v_exp_f32_e32 v248, v248
	v_exp_f32_e32 v249, v249
	v_add_f32_e32 v242, 1.0, v242
	v_add_f32_e32 v243, 1.0, v243
	v_add_f32_e32 v244, 1.0, v244
	v_add_f32_e32 v245, 1.0, v245
	s_waitcnt lgkmcnt(2)
	v_mfma_f32_32x32x16_bf16 v[48:63], v[88:91], v[200:203], v[48:63]
	v_add_f32_e32 v246, 1.0, v246
	v_add_f32_e32 v247, 1.0, v247
	v_add_f32_e32 v248, 1.0, v248
	v_add_f32_e32 v249, 1.0, v249
	v_rcp_f32_e32 v242, v242
	v_rcp_f32_e32 v243, v243
	v_rcp_f32_e32 v244, v244
	v_rcp_f32_e32 v245, v245
	s_waitcnt lgkmcnt(1)
	v_mfma_f32_32x32x16_bf16 v[48:63], v[96:99], v[204:207], v[48:63]
	v_rcp_f32_e32 v246, v246
	v_rcp_f32_e32 v247, v247
	v_rcp_f32_e32 v248, v248
	v_rcp_f32_e32 v249, v249
	v_mul_f32_e32 v234, v234, v242
	v_mul_f32_e32 v235, v235, v243
	v_mul_f32_e32 v236, v236, v244
	v_mul_f32_e32 v237, v237, v245
	s_waitcnt lgkmcnt(0)
	v_mfma_f32_32x32x16_bf16 v[48:63], v[108:111], v[208:211], v[48:63]
	v_mul_f32_e32 v238, v238, v246
	v_mul_f32_e32 v239, v239, v247
	v_mul_f32_e32 v240, v240, v248
	v_mul_f32_e32 v241, v241, v249
	v_cvt_pk_bf16_f32 v242, v234, v235
	v_cvt_pk_bf16_f32 v243, v236, v237
	v_cvt_pk_bf16_f32 v244, v238, v239
	v_cvt_pk_bf16_f32 v245, v240, v241
	s_cmp_eq_u32 s16, 0x800
	s_cbranch_scc1 .Lscan_nostore
	global_store_dwordx2 v253, v[242:243], s[14:15]
	global_store_dwordx2 v254, v[244:245], s[14:15]
	s_movk_i32 s18, 0x1000
	s_and_b32 s17, s16, 0x3800
	s_cmp_eq_u32 s17, 0x800
	s_cselect_b32 s18, 0x1f9000, s18
	s_add_u32 s14, s14, s18
	s_addc_u32 s15, s15, 0

.Lscan_go_1:
	v_mfma_f32_32x32x16_bf16 v[0:15], v[168:171], v[104:107], 0
	s_addk_i32 s16, 0x800
	v_mfma_f32_32x32x16_bf16 v[16:31], v[168:171], v[116:119], 0
	v_mfma_f32_32x32x16_bf16 v[32:47], v[168:171], v[92:95], 0
	v_mfma_f32_32x32x16_bf16 v[196:211], v[168:171], v[112:115], 0
	v_mov_b32_e32 v218, v168
	v_mov_b32_e32 v220, v170
	v_mov_b32_e32 v219, v169
	v_mov_b32_e32 v221, v171
	v_permlane32_swap_b32_e32 v218, v220
	s_add_u32 s0, s0, 0x40000
	s_addc_u32 s1, s1, 0
	v_permlane32_swap_b32_e32 v219, v221
	v_lshl_add_u64 v[216:217], v[152:153], 0, s[0:1]
	global_load_dwordx4 v[168:171], v[216:217], off
	v_lshlrev_b32_e32 v162, 16, v218
	v_and_b32_e32 v163, 0xffff0000, v218
	v_lshlrev_b32_e32 v164, 16, v219
	v_and_b32_e32 v165, 0xffff0000, v219
	v_lshlrev_b32_e32 v166, 16, v220
	v_and_b32_e32 v167, 0xffff0000, v220
	v_lshlrev_b32_e32 v192, 16, v221
	v_and_b32_e32 v193, 0xffff0000, v221
	v_permlane32_swap_b32_e32 v0, v16
	v_permlane32_swap_b32_e32 v1, v17
	v_permlane32_swap_b32_e32 v2, v18
	v_permlane32_swap_b32_e32 v3, v19
	v_permlane32_swap_b32_e32 v4, v20
	v_permlane32_swap_b32_e32 v5, v21
	v_permlane32_swap_b32_e32 v6, v22
	v_permlane32_swap_b32_e32 v7, v23
	v_permlane32_swap_b32_e32 v8, v24
	v_permlane32_swap_b32_e32 v9, v25
	v_permlane32_swap_b32_e32 v10, v26
	v_permlane32_swap_b32_e32 v11, v27
	v_permlane32_swap_b32_e32 v12, v28
	v_permlane32_swap_b32_e32 v13, v29
	v_permlane32_swap_b32_e32 v14, v30
	v_permlane32_swap_b32_e32 v15, v31
	v_permlane32_swap_b32_e32 v32, v196
	v_permlane32_swap_b32_e32 v33, v197
	v_permlane32_swap_b32_e32 v34, v198
	v_permlane32_swap_b32_e32 v35, v199
	v_permlane32_swap_b32_e32 v36, v200
	v_permlane32_swap_b32_e32 v37, v201
	v_permlane32_swap_b32_e32 v38, v202
	v_permlane32_swap_b32_e32 v39, v203
	v_permlane32_swap_b32_e32 v40, v204
	v_permlane32_swap_b32_e32 v41, v205
	v_permlane32_swap_b32_e32 v42, v206
	v_permlane32_swap_b32_e32 v43, v207
	v_permlane32_swap_b32_e32 v44, v208
	v_permlane32_swap_b32_e32 v45, v209
	v_permlane32_swap_b32_e32 v46, v210
	v_permlane32_swap_b32_e32 v47, v211
	v_fmac_f32_e32 v0, v160, v188
	v_fmac_f32_e32 v32, v160, v189
	v_fma_f32 v0, -v161, v189, v0
	v_fmac_f32_e32 v32, v161, v188
	v_fmac_f32_e32 v1, v160, v0
	v_fmac_f32_e32 v33, v160, v32
	v_cvt_pk_bf16_f32 v212, v0, v32
	v_fma_f32 v1, -v161, v32, v1
	v_fmac_f32_e32 v33, v161, v0
	v_fmac_f32_e32 v2, v160, v1
	v_fmac_f32_e32 v34, v160, v33
	v_cvt_pk_bf16_f32 v213, v1, v33
	v_fma_f32 v2, -v161, v33, v2
	v_fmac_f32_e32 v34, v161, v1
	ds_write2_b32 v222, v212, v213 offset0:0 offset1:68
	v_fmac_f32_e32 v3, v160, v2
	v_fmac_f32_e32 v35, v160, v34
	v_cvt_pk_bf16_f32 v214, v2, v34
	v_fma_f32 v3, -v161, v34, v3
	v_fmac_f32_e32 v35, v161, v2
	v_fmac_f32_e32 v16, v160, v3
	v_fmac_f32_e32 v196, v160, v35
	v_cvt_pk_bf16_f32 v215, v3, v35
	v_fma_f32 v16, -v161, v35, v16
	v_fmac_f32_e32 v196, v161, v3
	ds_write2_b32 v222, v214, v215 offset0:136 offset1:204
	v_fmac_f32_e32 v17, v160, v16
	v_fmac_f32_e32 v197, v160, v196
	v_cvt_pk_bf16_f32 v212, v16, v196
	v_fma_f32 v17, -v161, v196, v17
	v_fmac_f32_e32 v197, v161, v16
	v_fmac_f32_e32 v18, v160, v17
	v_fmac_f32_e32 v198, v160, v197
	v_cvt_pk_bf16_f32 v213, v17, v197
	v_fma_f32 v18, -v161, v197, v18
	v_fmac_f32_e32 v198, v161, v17
	ds_write2_b32 v223, v212, v213 offset0:0 offset1:68
	v_fmac_f32_e32 v19, v160, v18
	v_fmac_f32_e32 v199, v160, v198
	v_cvt_pk_bf16_f32 v214, v18, v198
	v_fma_f32 v19, -v161, v198, v19
	v_fmac_f32_e32 v199, v161, v18
	v_fmac_f32_e32 v4, v160, v19
	v_fmac_f32_e32 v36, v160, v199
	v_cvt_pk_bf16_f32 v215, v19, v199
	v_fma_f32 v4, -v161, v199, v4
	v_fmac_f32_e32 v36, v161, v19
	ds_write2_b32 v223, v214, v215 offset0:136 offset1:204
	v_fmac_f32_e32 v5, v160, v4
	v_fmac_f32_e32 v37, v160, v36
	v_cvt_pk_bf16_f32 v212, v4, v36
	v_fma_f32 v5, -v161, v36, v5
	v_fmac_f32_e32 v37, v161, v4
	v_fmac_f32_e32 v6, v160, v5
	v_fmac_f32_e32 v38, v160, v37
	v_cvt_pk_bf16_f32 v213, v5, v37
	v_fma_f32 v6, -v161, v37, v6
	v_fmac_f32_e32 v38, v161, v5
	ds_write2_b32 v224, v212, v213 offset0:0 offset1:68
	v_fmac_f32_e32 v7, v160, v6
	v_fmac_f32_e32 v39, v160, v38
	v_cvt_pk_bf16_f32 v214, v6, v38
	v_fma_f32 v7, -v161, v38, v7
	v_fmac_f32_e32 v39, v161, v6
	v_fmac_f32_e32 v20, v160, v7
	v_fmac_f32_e32 v200, v160, v39
	v_cvt_pk_bf16_f32 v215, v7, v39
	v_fma_f32 v20, -v161, v39, v20
	v_fmac_f32_e32 v200, v161, v7
	ds_write2_b32 v224, v214, v215 offset0:136 offset1:204
	v_fmac_f32_e32 v21, v160, v20
	v_fmac_f32_e32 v201, v160, v200
	v_cvt_pk_bf16_f32 v212, v20, v200
	v_fma_f32 v21, -v161, v200, v21
	v_fmac_f32_e32 v201, v161, v20
	v_fmac_f32_e32 v22, v160, v21
	v_fmac_f32_e32 v202, v160, v201
	v_cvt_pk_bf16_f32 v213, v21, v201
	v_fma_f32 v22, -v161, v201, v22
	v_fmac_f32_e32 v202, v161, v21
	ds_write2_b32 v225, v212, v213 offset0:0 offset1:68
	v_fmac_f32_e32 v23, v160, v22
	v_fmac_f32_e32 v203, v160, v202
	v_cvt_pk_bf16_f32 v214, v22, v202
	v_fma_f32 v23, -v161, v202, v23
	v_fmac_f32_e32 v203, v161, v22
	v_fmac_f32_e32 v8, v160, v23
	v_fmac_f32_e32 v40, v160, v203
	v_cvt_pk_bf16_f32 v215, v23, v203
	v_fma_f32 v8, -v161, v203, v8
	v_fmac_f32_e32 v40, v161, v23
	ds_write2_b32 v225, v214, v215 offset0:136 offset1:204
	v_fmac_f32_e32 v9, v160, v8
	v_fmac_f32_e32 v41, v160, v40
	v_cvt_pk_bf16_f32 v212, v8, v40
	v_fma_f32 v9, -v161, v40, v9
	v_fmac_f32_e32 v41, v161, v8
	v_fmac_f32_e32 v10, v160, v9
	v_fmac_f32_e32 v42, v160, v41
	v_cvt_pk_bf16_f32 v213, v9, v41
	v_fma_f32 v10, -v161, v41, v10
	v_fmac_f32_e32 v42, v161, v9
	ds_write2_b32 v226, v212, v213 offset0:0 offset1:68
	v_fmac_f32_e32 v11, v160, v10
	v_fmac_f32_e32 v43, v160, v42
	v_cvt_pk_bf16_f32 v214, v10, v42
	v_fma_f32 v11, -v161, v42, v11
	v_fmac_f32_e32 v43, v161, v10
	v_fmac_f32_e32 v24, v160, v11
	v_fmac_f32_e32 v204, v160, v43
	v_cvt_pk_bf16_f32 v215, v11, v43
	v_fma_f32 v24, -v161, v43, v24
	v_fmac_f32_e32 v204, v161, v11
	ds_write2_b32 v226, v214, v215 offset0:136 offset1:204
	v_fmac_f32_e32 v25, v160, v24
	v_fmac_f32_e32 v205, v160, v204
	v_cvt_pk_bf16_f32 v212, v24, v204
	v_fma_f32 v25, -v161, v204, v25
	v_fmac_f32_e32 v205, v161, v24
	v_fmac_f32_e32 v26, v160, v25
	v_fmac_f32_e32 v206, v160, v205
	v_cvt_pk_bf16_f32 v213, v25, v205
	v_fma_f32 v26, -v161, v205, v26
	v_fmac_f32_e32 v206, v161, v25
	ds_write2_b32 v227, v212, v213 offset0:0 offset1:68
	v_fmac_f32_e32 v27, v160, v26
	v_fmac_f32_e32 v207, v160, v206
	v_cvt_pk_bf16_f32 v214, v26, v206
	v_fma_f32 v27, -v161, v206, v27
	v_fmac_f32_e32 v207, v161, v26
	v_fmac_f32_e32 v12, v160, v27
	v_fmac_f32_e32 v44, v160, v207
	v_cvt_pk_bf16_f32 v215, v27, v207
	v_fma_f32 v12, -v161, v207, v12
	v_fmac_f32_e32 v44, v161, v27
	ds_write2_b32 v227, v214, v215 offset0:136 offset1:204
	v_fmac_f32_e32 v13, v160, v12
	v_fmac_f32_e32 v45, v160, v44
	v_cvt_pk_bf16_f32 v212, v12, v44
	v_fma_f32 v13, -v161, v44, v13
	v_fmac_f32_e32 v45, v161, v12
	v_fmac_f32_e32 v14, v160, v13
	v_fmac_f32_e32 v46, v160, v45
	v_cvt_pk_bf16_f32 v213, v13, v45
	v_fma_f32 v14, -v161, v45, v14
	v_fmac_f32_e32 v46, v161, v13
	ds_write2_b32 v190, v212, v213 offset0:0 offset1:68
	v_fmac_f32_e32 v15, v160, v14
	v_fmac_f32_e32 v47, v160, v46
	v_cvt_pk_bf16_f32 v214, v14, v46
	v_fma_f32 v15, -v161, v46, v15
	v_fmac_f32_e32 v47, v161, v14
	v_fmac_f32_e32 v28, v160, v15
	v_fmac_f32_e32 v208, v160, v47
	v_cvt_pk_bf16_f32 v215, v15, v47
	v_fma_f32 v28, -v161, v47, v28
	v_fmac_f32_e32 v208, v161, v15
	ds_write2_b32 v190, v214, v215 offset0:136 offset1:204
	v_fmac_f32_e32 v29, v160, v28
	v_fmac_f32_e32 v209, v160, v208
	v_cvt_pk_bf16_f32 v212, v28, v208
	v_fma_f32 v29, -v161, v208, v29
	v_fmac_f32_e32 v209, v161, v28
	v_fmac_f32_e32 v30, v160, v29
	v_fmac_f32_e32 v210, v160, v209
	v_cvt_pk_bf16_f32 v213, v29, v209
	v_fma_f32 v30, -v161, v209, v30
	v_fmac_f32_e32 v210, v161, v29
	ds_write2_b32 v191, v212, v213 offset0:0 offset1:68
	v_fmac_f32_e32 v31, v160, v30
	v_fmac_f32_e32 v211, v160, v210
	v_cvt_pk_bf16_f32 v214, v30, v210
	v_fma_f32 v31, -v161, v210, v31
	v_fmac_f32_e32 v211, v161, v30
	v_mov_b32_e32 v188, v31
	v_mov_b32_e32 v189, v211
	v_cvt_pk_bf16_f32 v215, v31, v211
	ds_write2_b32 v191, v214, v215 offset0:136 offset1:204
	s_waitcnt lgkmcnt(0)
	ds_read_b128 v[32:35], v186 offset:18432
	ds_read_b128 v[36:39], v186 offset:18464
	ds_read_b128 v[40:43], v186 offset:18496
	ds_read_b128 v[44:47], v186 offset:18528
	ds_read_b128 v[196:199], v186 offset:18560
	ds_read_b128 v[200:203], v186 offset:18592
	ds_read_b128 v[204:207], v186 offset:18624
	ds_read_b128 v[208:211], v186 offset:18656
	s_waitcnt lgkmcnt(7)
	v_mfma_f32_32x32x16_bf16 v[234:249], v[64:67], v[32:35], 0
	v_fmac_f32_e32 v48, v100, v228
	v_fmac_f32_e32 v49, v101, v229
	v_fmac_f32_e32 v50, v102, v230
	v_fmac_f32_e32 v51, v103, v231
	v_fmac_f32_e32 v52, v80, v232
	v_fmac_f32_e32 v53, v81, v233
	v_fmac_f32_e32 v54, v82, v251
	v_fmac_f32_e32 v55, v83, v252
	v_mul_f32_e32 v56, v48, v48
	s_waitcnt lgkmcnt(6)
	v_mfma_f32_32x32x16_bf16 v[234:249], v[68:71], v[36:39], v[234:249]
	v_mul_f32_e32 v57, v49, v49
	v_mul_f32_e32 v58, v50, v50
	v_mul_f32_e32 v59, v51, v51
	v_mul_f32_e32 v60, v52, v52
	v_mul_f32_e32 v61, v53, v53
	v_mul_f32_e32 v62, v54, v54
	v_mul_f32_e32 v63, v55, v55
	v_fmaak_f32 v56, v56, v184, 0xc0135761
	v_fmaak_f32 v57, v57, v184, 0xc0135761
	s_waitcnt lgkmcnt(5)
	v_mfma_f32_32x32x16_bf16 v[234:249], v[72:75], v[40:43], v[234:249]
	v_fmaak_f32 v58, v58, v184, 0xc0135761
	v_fmaak_f32 v59, v59, v184, 0xc0135761
	v_fmaak_f32 v60, v60, v184, 0xc0135761
	v_fmaak_f32 v61, v61, v184, 0xc0135761
	v_fmaak_f32 v62, v62, v184, 0xc0135761
	v_fmaak_f32 v63, v63, v184, 0xc0135761
	v_mul_f32_e32 v56, v48, v56
	v_mul_f32_e32 v57, v49, v57
	v_mul_f32_e32 v58, v50, v58
	s_waitcnt lgkmcnt(4)
	v_mfma_f32_32x32x16_bf16 v[234:249], v[76:79], v[44:47], v[234:249]
	v_mul_f32_e32 v59, v51, v59
	v_mul_f32_e32 v60, v52, v60
	v_mul_f32_e32 v61, v53, v61
	v_mul_f32_e32 v62, v54, v62
	v_mul_f32_e32 v63, v55, v63
	v_exp_f32_e32 v56, v56
	v_exp_f32_e32 v57, v57
	v_exp_f32_e32 v58, v58
	v_exp_f32_e32 v59, v59
	s_waitcnt lgkmcnt(3)
	v_mfma_f32_32x32x16_bf16 v[234:249], v[84:87], v[196:199], v[234:249]
	v_exp_f32_e32 v60, v60
	v_exp_f32_e32 v61, v61
	v_exp_f32_e32 v62, v62
	v_exp_f32_e32 v63, v63
	v_add_f32_e32 v56, 1.0, v56
	v_add_f32_e32 v57, 1.0, v57
	v_add_f32_e32 v58, 1.0, v58
	v_add_f32_e32 v59, 1.0, v59
	s_waitcnt lgkmcnt(2)
	v_mfma_f32_32x32x16_bf16 v[234:249], v[88:91], v[200:203], v[234:249]
	v_add_f32_e32 v60, 1.0, v60
	v_add_f32_e32 v61, 1.0, v61
	v_add_f32_e32 v62, 1.0, v62
	v_add_f32_e32 v63, 1.0, v63
	v_rcp_f32_e32 v56, v56
	v_rcp_f32_e32 v57, v57
	v_rcp_f32_e32 v58, v58
	v_rcp_f32_e32 v59, v59
	s_waitcnt lgkmcnt(1)
	v_mfma_f32_32x32x16_bf16 v[234:249], v[96:99], v[204:207], v[234:249]
	v_rcp_f32_e32 v60, v60
	v_rcp_f32_e32 v61, v61
	v_rcp_f32_e32 v62, v62
	v_rcp_f32_e32 v63, v63
	v_mul_f32_e32 v48, v48, v56
	v_mul_f32_e32 v49, v49, v57
	v_mul_f32_e32 v50, v50, v58
	v_mul_f32_e32 v51, v51, v59
	s_waitcnt lgkmcnt(0)
	v_mfma_f32_32x32x16_bf16 v[234:249], v[108:111], v[208:211], v[234:249]
	v_mul_f32_e32 v52, v52, v60
	v_mul_f32_e32 v53, v53, v61
	v_mul_f32_e32 v54, v54, v62
	v_mul_f32_e32 v55, v55, v63
	v_cvt_pk_bf16_f32 v56, v48, v49
	v_cvt_pk_bf16_f32 v57, v50, v51
	v_cvt_pk_bf16_f32 v58, v52, v53
	v_cvt_pk_bf16_f32 v59, v54, v55
	global_store_dwordx2 v253, v[56:57], s[14:15]
	global_store_dwordx2 v254, v[58:59], s[14:15]
	s_movk_i32 s18, 0x1000
	s_and_b32 s17, s16, 0x3800
	s_cmp_eq_u32 s17, 0x800
	s_cselect_b32 s18, 0x1f9000, s18
	s_add_u32 s14, s14, s18
	s_addc_u32 s15, s15, 0
	s_cmp_lt_u32 s16, 0x2800
	s_cbranch_scc1 .Lscan_w3_2
	s_waitcnt vmcnt(11)
.Lscan_go_2:
	v_mfma_f32_32x32x16_bf16 v[0:15], v[156:159], v[104:107], 0
	s_addk_i32 s16, 0x800
	v_mfma_f32_32x32x16_bf16 v[16:31], v[156:159], v[116:119], 0
	v_mfma_f32_32x32x16_bf16 v[32:47], v[156:159], v[92:95], 0
	v_mfma_f32_32x32x16_bf16 v[196:211], v[156:159], v[112:115], 0
	v_mov_b32_e32 v218, v156
	v_mov_b32_e32 v220, v158
	v_mov_b32_e32 v219, v157
	v_mov_b32_e32 v221, v159
	v_permlane32_swap_b32_e32 v218, v220
	s_add_u32 s0, s0, 0x40000
	s_addc_u32 s1, s1, 0
	v_permlane32_swap_b32_e32 v219, v221
	v_lshl_add_u64 v[216:217], v[152:153], 0, s[0:1]
	global_load_dwordx4 v[156:159], v[216:217], off
	v_lshlrev_b32_e32 v228, 16, v218
	v_and_b32_e32 v229, 0xffff0000, v218
	v_lshlrev_b32_e32 v230, 16, v219
	v_and_b32_e32 v231, 0xffff0000, v219
	v_lshlrev_b32_e32 v232, 16, v220
	v_and_b32_e32 v233, 0xffff0000, v220
	v_lshlrev_b32_e32 v251, 16, v221
	v_and_b32_e32 v252, 0xffff0000, v221
	v_permlane32_swap_b32_e32 v0, v16
	v_permlane32_swap_b32_e32 v1, v17
	v_permlane32_swap_b32_e32 v2, v18
	v_permlane32_swap_b32_e32 v3, v19
	v_permlane32_swap_b32_e32 v4, v20
	v_permlane32_swap_b32_e32 v5, v21
	v_permlane32_swap_b32_e32 v6, v22
	v_permlane32_swap_b32_e32 v7, v23
	v_permlane32_swap_b32_e32 v8, v24
	v_permlane32_swap_b32_e32 v9, v25
	v_permlane32_swap_b32_e32 v10, v26
	v_permlane32_swap_b32_e32 v11, v27
	v_permlane32_swap_b32_e32 v12, v28
	v_permlane32_swap_b32_e32 v13, v29
	v_permlane32_swap_b32_e32 v14, v30
	v_permlane32_swap_b32_e32 v15, v31
	v_permlane32_swap_b32_e32 v32, v196
	v_permlane32_swap_b32_e32 v33, v197
	v_permlane32_swap_b32_e32 v34, v198
	v_permlane32_swap_b32_e32 v35, v199
	v_permlane32_swap_b32_e32 v36, v200
	v_permlane32_swap_b32_e32 v37, v201
	v_permlane32_swap_b32_e32 v38, v202
	v_permlane32_swap_b32_e32 v39, v203
	v_permlane32_swap_b32_e32 v40, v204
	v_permlane32_swap_b32_e32 v41, v205
	v_permlane32_swap_b32_e32 v42, v206
	v_permlane32_swap_b32_e32 v43, v207
	v_permlane32_swap_b32_e32 v44, v208
	v_permlane32_swap_b32_e32 v45, v209
	v_permlane32_swap_b32_e32 v46, v210
	v_permlane32_swap_b32_e32 v47, v211
	v_fmac_f32_e32 v0, v160, v188
	v_fmac_f32_e32 v32, v160, v189
	v_fma_f32 v0, -v161, v189, v0
	v_fmac_f32_e32 v32, v161, v188
	v_fmac_f32_e32 v1, v160, v0
	v_fmac_f32_e32 v33, v160, v32
	v_cvt_pk_bf16_f32 v212, v0, v32
	v_fma_f32 v1, -v161, v32, v1
	v_fmac_f32_e32 v33, v161, v0
	v_fmac_f32_e32 v2, v160, v1
	v_fmac_f32_e32 v34, v160, v33
	v_cvt_pk_bf16_f32 v213, v1, v33
	v_fma_f32 v2, -v161, v33, v2
	v_fmac_f32_e32 v34, v161, v1
	ds_write2_b32 v222, v212, v213 offset0:0 offset1:68
	v_fmac_f32_e32 v3, v160, v2
	v_fmac_f32_e32 v35, v160, v34
	v_cvt_pk_bf16_f32 v214, v2, v34
	v_fma_f32 v3, -v161, v34, v3
	v_fmac_f32_e32 v35, v161, v2
	v_fmac_f32_e32 v16, v160, v3
	v_fmac_f32_e32 v196, v160, v35
	v_cvt_pk_bf16_f32 v215, v3, v35
	v_fma_f32 v16, -v161, v35, v16
	v_fmac_f32_e32 v196, v161, v3
	ds_write2_b32 v222, v214, v215 offset0:136 offset1:204
	v_fmac_f32_e32 v17, v160, v16
	v_fmac_f32_e32 v197, v160, v196
	v_cvt_pk_bf16_f32 v212, v16, v196
	v_fma_f32 v17, -v161, v196, v17
	v_fmac_f32_e32 v197, v161, v16
	v_fmac_f32_e32 v18, v160, v17
	v_fmac_f32_e32 v198, v160, v197
	v_cvt_pk_bf16_f32 v213, v17, v197
	v_fma_f32 v18, -v161, v197, v18
	v_fmac_f32_e32 v198, v161, v17
	ds_write2_b32 v223, v212, v213 offset0:0 offset1:68
	v_fmac_f32_e32 v19, v160, v18
	v_fmac_f32_e32 v199, v160, v198
	v_cvt_pk_bf16_f32 v214, v18, v198
	v_fma_f32 v19, -v161, v198, v19
	v_fmac_f32_e32 v199, v161, v18
	v_fmac_f32_e32 v4, v160, v19
	v_fmac_f32_e32 v36, v160, v199
	v_cvt_pk_bf16_f32 v215, v19, v199
	v_fma_f32 v4, -v161, v199, v4
	v_fmac_f32_e32 v36, v161, v19
	ds_write2_b32 v223, v214, v215 offset0:136 offset1:204
	v_fmac_f32_e32 v5, v160, v4
	v_fmac_f32_e32 v37, v160, v36
	v_cvt_pk_bf16_f32 v212, v4, v36
	v_fma_f32 v5, -v161, v36, v5
	v_fmac_f32_e32 v37, v161, v4
	v_fmac_f32_e32 v6, v160, v5
	v_fmac_f32_e32 v38, v160, v37
	v_cvt_pk_bf16_f32 v213, v5, v37
	v_fma_f32 v6, -v161, v37, v6
	v_fmac_f32_e32 v38, v161, v5
	ds_write2_b32 v224, v212, v213 offset0:0 offset1:68
	v_fmac_f32_e32 v7, v160, v6
	v_fmac_f32_e32 v39, v160, v38
	v_cvt_pk_bf16_f32 v214, v6, v38
	v_fma_f32 v7, -v161, v38, v7
	v_fmac_f32_e32 v39, v161, v6
	v_fmac_f32_e32 v20, v160, v7
	v_fmac_f32_e32 v200, v160, v39
	v_cvt_pk_bf16_f32 v215, v7, v39
	v_fma_f32 v20, -v161, v39, v20
	v_fmac_f32_e32 v200, v161, v7
	ds_write2_b32 v224, v214, v215 offset0:136 offset1:204
	v_fmac_f32_e32 v21, v160, v20
	v_fmac_f32_e32 v201, v160, v200
	v_cvt_pk_bf16_f32 v212, v20, v200
	v_fma_f32 v21, -v161, v200, v21
	v_fmac_f32_e32 v201, v161, v20
	v_fmac_f32_e32 v22, v160, v21
	v_fmac_f32_e32 v202, v160, v201
	v_cvt_pk_bf16_f32 v213, v21, v201
	v_fma_f32 v22, -v161, v201, v22
	v_fmac_f32_e32 v202, v161, v21
	ds_write2_b32 v225, v212, v213 offset0:0 offset1:68
	v_fmac_f32_e32 v23, v160, v22
	v_fmac_f32_e32 v203, v160, v202
	v_cvt_pk_bf16_f32 v214, v22, v202
	v_fma_f32 v23, -v161, v202, v23
	v_fmac_f32_e32 v203, v161, v22
	v_fmac_f32_e32 v8, v160, v23
	v_fmac_f32_e32 v40, v160, v203
	v_cvt_pk_bf16_f32 v215, v23, v203
	v_fma_f32 v8, -v161, v203, v8
	v_fmac_f32_e32 v40, v161, v23
	ds_write2_b32 v225, v214, v215 offset0:136 offset1:204
	v_fmac_f32_e32 v9, v160, v8
	v_fmac_f32_e32 v41, v160, v40
	v_cvt_pk_bf16_f32 v212, v8, v40
	v_fma_f32 v9, -v161, v40, v9
	v_fmac_f32_e32 v41, v161, v8
	v_fmac_f32_e32 v10, v160, v9
	v_fmac_f32_e32 v42, v160, v41
	v_cvt_pk_bf16_f32 v213, v9, v41
	v_fma_f32 v10, -v161, v41, v10
	v_fmac_f32_e32 v42, v161, v9
	ds_write2_b32 v226, v212, v213 offset0:0 offset1:68
	v_fmac_f32_e32 v11, v160, v10
	v_fmac_f32_e32 v43, v160, v42
	v_cvt_pk_bf16_f32 v214, v10, v42
	v_fma_f32 v11, -v161, v42, v11
	v_fmac_f32_e32 v43, v161, v10
	v_fmac_f32_e32 v24, v160, v11
	v_fmac_f32_e32 v204, v160, v43
	v_cvt_pk_bf16_f32 v215, v11, v43
	v_fma_f32 v24, -v161, v43, v24
	v_fmac_f32_e32 v204, v161, v11
	ds_write2_b32 v226, v214, v215 offset0:136 offset1:204
	v_fmac_f32_e32 v25, v160, v24
	v_fmac_f32_e32 v205, v160, v204
	v_cvt_pk_bf16_f32 v212, v24, v204
	v_fma_f32 v25, -v161, v204, v25
	v_fmac_f32_e32 v205, v161, v24
	v_fmac_f32_e32 v26, v160, v25
	v_fmac_f32_e32 v206, v160, v205
	v_cvt_pk_bf16_f32 v213, v25, v205
	v_fma_f32 v26, -v161, v205, v26
	v_fmac_f32_e32 v206, v161, v25
	ds_write2_b32 v227, v212, v213 offset0:0 offset1:68
	v_fmac_f32_e32 v27, v160, v26
	v_fmac_f32_e32 v207, v160, v206
	v_cvt_pk_bf16_f32 v214, v26, v206
	v_fma_f32 v27, -v161, v206, v27
	v_fmac_f32_e32 v207, v161, v26
	v_fmac_f32_e32 v12, v160, v27
	v_fmac_f32_e32 v44, v160, v207
	v_cvt_pk_bf16_f32 v215, v27, v207
	v_fma_f32 v12, -v161, v207, v12
	v_fmac_f32_e32 v44, v161, v27
	ds_write2_b32 v227, v214, v215 offset0:136 offset1:204
	v_fmac_f32_e32 v13, v160, v12
	v_fmac_f32_e32 v45, v160, v44
	v_cvt_pk_bf16_f32 v212, v12, v44
	v_fma_f32 v13, -v161, v44, v13
	v_fmac_f32_e32 v45, v161, v12
	v_fmac_f32_e32 v14, v160, v13
	v_fmac_f32_e32 v46, v160, v45
	v_cvt_pk_bf16_f32 v213, v13, v45
	v_fma_f32 v14, -v161, v45, v14
	v_fmac_f32_e32 v46, v161, v13
	ds_write2_b32 v190, v212, v213 offset0:0 offset1:68
	v_fmac_f32_e32 v15, v160, v14
	v_fmac_f32_e32 v47, v160, v46
	v_cvt_pk_bf16_f32 v214, v14, v46
	v_fma_f32 v15, -v161, v46, v15
	v_fmac_f32_e32 v47, v161, v14
	v_fmac_f32_e32 v28, v160, v15
	v_fmac_f32_e32 v208, v160, v47
	v_cvt_pk_bf16_f32 v215, v15, v47
	v_fma_f32 v28, -v161, v47, v28
	v_fmac_f32_e32 v208, v161, v15
	ds_write2_b32 v190, v214, v215 offset0:136 offset1:204
	v_fmac_f32_e32 v29, v160, v28
	v_fmac_f32_e32 v209, v160, v208
	v_cvt_pk_bf16_f32 v212, v28, v208
	v_fma_f32 v29, -v161, v208, v29
	v_fmac_f32_e32 v209, v161, v28
	v_fmac_f32_e32 v30, v160, v29
	v_fmac_f32_e32 v210, v160, v209
	v_cvt_pk_bf16_f32 v213, v29, v209
	v_fma_f32 v30, -v161, v209, v30
	v_fmac_f32_e32 v210, v161, v29
	ds_write2_b32 v191, v212, v213 offset0:0 offset1:68
	v_fmac_f32_e32 v31, v160, v30
	v_fmac_f32_e32 v211, v160, v210
	v_cvt_pk_bf16_f32 v214, v30, v210
	v_fma_f32 v31, -v161, v210, v31
	v_fmac_f32_e32 v211, v161, v30
	v_mov_b32_e32 v188, v31
	v_mov_b32_e32 v189, v211
	v_cvt_pk_bf16_f32 v215, v31, v211
	ds_write2_b32 v191, v214, v215 offset0:136 offset1:204
	s_waitcnt lgkmcnt(0)
	ds_read_b128 v[32:35], v186 offset:18432
	ds_read_b128 v[36:39], v186 offset:18464
	ds_read_b128 v[40:43], v186 offset:18496
	ds_read_b128 v[44:47], v186 offset:18528
	ds_read_b128 v[196:199], v186 offset:18560
	ds_read_b128 v[200:203], v186 offset:18592
	ds_read_b128 v[204:207], v186 offset:18624
	ds_read_b128 v[208:211], v186 offset:18656
	s_waitcnt lgkmcnt(7)
	v_mfma_f32_32x32x16_bf16 v[48:63], v[64:67], v[32:35], 0
	v_fmac_f32_e32 v234, v100, v162
	v_fmac_f32_e32 v235, v101, v163
	v_fmac_f32_e32 v236, v102, v164
	v_fmac_f32_e32 v237, v103, v165
	v_fmac_f32_e32 v238, v80, v166
	v_fmac_f32_e32 v239, v81, v167
	v_fmac_f32_e32 v240, v82, v192
	v_fmac_f32_e32 v241, v83, v193
	v_mul_f32_e32 v242, v234, v234
	s_waitcnt lgkmcnt(6)
	v_mfma_f32_32x32x16_bf16 v[48:63], v[68:71], v[36:39], v[48:63]
	v_mul_f32_e32 v243, v235, v235
	v_mul_f32_e32 v244, v236, v236
	v_mul_f32_e32 v245, v237, v237
	v_mul_f32_e32 v246, v238, v238
	v_mul_f32_e32 v247, v239, v239
	v_mul_f32_e32 v248, v240, v240
	v_mul_f32_e32 v249, v241, v241
	v_fmaak_f32 v242, v242, v184, 0xc0135761
	v_fmaak_f32 v243, v243, v184, 0xc0135761
	s_waitcnt lgkmcnt(5)
	v_mfma_f32_32x32x16_bf16 v[48:63], v[72:75], v[40:43], v[48:63]
	v_fmaak_f32 v244, v244, v184, 0xc0135761
	v_fmaak_f32 v245, v245, v184, 0xc0135761
	v_fmaak_f32 v246, v246, v184, 0xc0135761
	v_fmaak_f32 v247, v247, v184, 0xc0135761
	v_fmaak_f32 v248, v248, v184, 0xc0135761
	v_fmaak_f32 v249, v249, v184, 0xc0135761
	v_mul_f32_e32 v242, v234, v242
	v_mul_f32_e32 v243, v235, v243
	v_mul_f32_e32 v244, v236, v244
	s_waitcnt lgkmcnt(4)
	v_mfma_f32_32x32x16_bf16 v[48:63], v[76:79], v[44:47], v[48:63]
	v_mul_f32_e32 v245, v237, v245
	v_mul_f32_e32 v246, v238, v246
	v_mul_f32_e32 v247, v239, v247
	v_mul_f32_e32 v248, v240, v248
	v_mul_f32_e32 v249, v241, v249
	v_exp_f32_e32 v242, v242
	v_exp_f32_e32 v243, v243
	v_exp_f32_e32 v244, v244
	v_exp_f32_e32 v245, v245
	s_waitcnt lgkmcnt(3)
	v_mfma_f32_32x32x16_bf16 v[48:63], v[84:87], v[196:199], v[48:63]
	v_exp_f32_e32 v246, v246
	v_exp_f32_e32 v247, v247
	v_exp_f32_e32 v248, v248
	v_exp_f32_e32 v249, v249
	v_add_f32_e32 v242, 1.0, v242
	v_add_f32_e32 v243, 1.0, v243
	v_add_f32_e32 v244, 1.0, v244
	v_add_f32_e32 v245, 1.0, v245
	s_waitcnt lgkmcnt(2)
	v_mfma_f32_32x32x16_bf16 v[48:63], v[88:91], v[200:203], v[48:63]
	v_add_f32_e32 v246, 1.0, v246
	v_add_f32_e32 v247, 1.0, v247
	v_add_f32_e32 v248, 1.0, v248
	v_add_f32_e32 v249, 1.0, v249
	v_rcp_f32_e32 v242, v242
	v_rcp_f32_e32 v243, v243
	v_rcp_f32_e32 v244, v244
	v_rcp_f32_e32 v245, v245
	s_waitcnt lgkmcnt(1)
	v_mfma_f32_32x32x16_bf16 v[48:63], v[96:99], v[204:207], v[48:63]
	v_rcp_f32_e32 v246, v246
	v_rcp_f32_e32 v247, v247
	v_rcp_f32_e32 v248, v248
	v_rcp_f32_e32 v249, v249
	v_mul_f32_e32 v234, v234, v242
	v_mul_f32_e32 v235, v235, v243
	v_mul_f32_e32 v236, v236, v244
	v_mul_f32_e32 v237, v237, v245
	s_waitcnt lgkmcnt(0)
	v_mfma_f32_32x32x16_bf16 v[48:63], v[108:111], v[208:211], v[48:63]
	v_mul_f32_e32 v238, v238, v246
	v_mul_f32_e32 v239, v239, v247
	v_mul_f32_e32 v240, v240, v248
	v_mul_f32_e32 v241, v241, v249
	v_cvt_pk_bf16_f32 v242, v234, v235
	v_cvt_pk_bf16_f32 v243, v236, v237
	v_cvt_pk_bf16_f32 v244, v238, v239
	v_cvt_pk_bf16_f32 v245, v240, v241
	global_store_dwordx2 v253, v[242:243], s[14:15]
	global_store_dwordx2 v254, v[244:245], s[14:15]
	s_movk_i32 s18, 0x1000
	s_and_b32 s17, s16, 0x3800
	s_cmp_eq_u32 s17, 0x800
	s_cselect_b32 s18, 0x1f9000, s18
	s_add_u32 s14, s14, s18
	s_addc_u32 s15, s15, 0
	s_cmp_lt_u32 s16, 0x2800
	s_cbranch_scc1 .Lscan_w3_3
	s_waitcnt vmcnt(11)
.Lscan_go_3:
	v_mfma_f32_32x32x16_bf16 v[0:15], v[178:181], v[104:107], 0
	s_addk_i32 s16, 0x800
	v_mfma_f32_32x32x16_bf16 v[16:31], v[178:181], v[116:119], 0
	v_mfma_f32_32x32x16_bf16 v[32:47], v[178:181], v[92:95], 0
	v_mfma_f32_32x32x16_bf16 v[196:211], v[178:181], v[112:115], 0
	v_mov_b32_e32 v218, v178
	v_mov_b32_e32 v220, v180
	v_mov_b32_e32 v219, v179
	v_mov_b32_e32 v221, v181
	v_permlane32_swap_b32_e32 v218, v220
	s_add_u32 s0, s0, 0x40000
	s_addc_u32 s1, s1, 0
	v_permlane32_swap_b32_e32 v219, v221
	v_lshl_add_u64 v[216:217], v[152:153], 0, s[0:1]
	global_load_dwordx4 v[178:181], v[216:217], off
	v_lshlrev_b32_e32 v162, 16, v218
	v_and_b32_e32 v163, 0xffff0000, v218
	v_lshlrev_b32_e32 v164, 16, v219
	v_and_b32_e32 v165, 0xffff0000, v219
	v_lshlrev_b32_e32 v166, 16, v220
	v_and_b32_e32 v167, 0xffff0000, v220
	v_lshlrev_b32_e32 v192, 16, v221
	v_and_b32_e32 v193, 0xffff0000, v221
	v_permlane32_swap_b32_e32 v0, v16
	v_permlane32_swap_b32_e32 v1, v17
	v_permlane32_swap_b32_e32 v2, v18
	v_permlane32_swap_b32_e32 v3, v19
	v_permlane32_swap_b32_e32 v4, v20
	v_permlane32_swap_b32_e32 v5, v21
	v_permlane32_swap_b32_e32 v6, v22
	v_permlane32_swap_b32_e32 v7, v23
	v_permlane32_swap_b32_e32 v8, v24
	v_permlane32_swap_b32_e32 v9, v25
	v_permlane32_swap_b32_e32 v10, v26
	v_permlane32_swap_b32_e32 v11, v27
	v_permlane32_swap_b32_e32 v12, v28
	v_permlane32_swap_b32_e32 v13, v29
	v_permlane32_swap_b32_e32 v14, v30
	v_permlane32_swap_b32_e32 v15, v31
	v_permlane32_swap_b32_e32 v32, v196
	v_permlane32_swap_b32_e32 v33, v197
	v_permlane32_swap_b32_e32 v34, v198
	v_permlane32_swap_b32_e32 v35, v199
	v_permlane32_swap_b32_e32 v36, v200
	v_permlane32_swap_b32_e32 v37, v201
	v_permlane32_swap_b32_e32 v38, v202
	v_permlane32_swap_b32_e32 v39, v203
	v_permlane32_swap_b32_e32 v40, v204
	v_permlane32_swap_b32_e32 v41, v205
	v_permlane32_swap_b32_e32 v42, v206
	v_permlane32_swap_b32_e32 v43, v207
	v_permlane32_swap_b32_e32 v44, v208
	v_permlane32_swap_b32_e32 v45, v209
	v_permlane32_swap_b32_e32 v46, v210
	v_permlane32_swap_b32_e32 v47, v211
	v_fmac_f32_e32 v0, v160, v188
	v_fmac_f32_e32 v32, v160, v189
	v_fma_f32 v0, -v161, v189, v0
	v_fmac_f32_e32 v32, v161, v188
	v_fmac_f32_e32 v1, v160, v0
	v_fmac_f32_e32 v33, v160, v32
	v_cvt_pk_bf16_f32 v212, v0, v32
	v_fma_f32 v1, -v161, v32, v1
	v_fmac_f32_e32 v33, v161, v0
	v_fmac_f32_e32 v2, v160, v1
	v_fmac_f32_e32 v34, v160, v33
	v_cvt_pk_bf16_f32 v213, v1, v33
	v_fma_f32 v2, -v161, v33, v2
	v_fmac_f32_e32 v34, v161, v1
	ds_write2_b32 v222, v212, v213 offset0:0 offset1:68
	v_fmac_f32_e32 v3, v160, v2
	v_fmac_f32_e32 v35, v160, v34
	v_cvt_pk_bf16_f32 v214, v2, v34
	v_fma_f32 v3, -v161, v34, v3
	v_fmac_f32_e32 v35, v161, v2
	v_fmac_f32_e32 v16, v160, v3
	v_fmac_f32_e32 v196, v160, v35
	v_cvt_pk_bf16_f32 v215, v3, v35
	v_fma_f32 v16, -v161, v35, v16
	v_fmac_f32_e32 v196, v161, v3
	ds_write2_b32 v222, v214, v215 offset0:136 offset1:204
	v_fmac_f32_e32 v17, v160, v16
	v_fmac_f32_e32 v197, v160, v196
	v_cvt_pk_bf16_f32 v212, v16, v196
	v_fma_f32 v17, -v161, v196, v17
	v_fmac_f32_e32 v197, v161, v16
	v_fmac_f32_e32 v18, v160, v17
	v_fmac_f32_e32 v198, v160, v197
	v_cvt_pk_bf16_f32 v213, v17, v197
	v_fma_f32 v18, -v161, v197, v18
	v_fmac_f32_e32 v198, v161, v17
	ds_write2_b32 v223, v212, v213 offset0:0 offset1:68
	v_fmac_f32_e32 v19, v160, v18
	v_fmac_f32_e32 v199, v160, v198
	v_cvt_pk_bf16_f32 v214, v18, v198
	v_fma_f32 v19, -v161, v198, v19
	v_fmac_f32_e32 v199, v161, v18
	v_fmac_f32_e32 v4, v160, v19
	v_fmac_f32_e32 v36, v160, v199
	v_cvt_pk_bf16_f32 v215, v19, v199
	v_fma_f32 v4, -v161, v199, v4
	v_fmac_f32_e32 v36, v161, v19
	ds_write2_b32 v223, v214, v215 offset0:136 offset1:204
	v_fmac_f32_e32 v5, v160, v4
	v_fmac_f32_e32 v37, v160, v36
	v_cvt_pk_bf16_f32 v212, v4, v36
	v_fma_f32 v5, -v161, v36, v5
	v_fmac_f32_e32 v37, v161, v4
	v_fmac_f32_e32 v6, v160, v5
	v_fmac_f32_e32 v38, v160, v37
	v_cvt_pk_bf16_f32 v213, v5, v37
	v_fma_f32 v6, -v161, v37, v6
	v_fmac_f32_e32 v38, v161, v5
	ds_write2_b32 v224, v212, v213 offset0:0 offset1:68
	v_fmac_f32_e32 v7, v160, v6
	v_fmac_f32_e32 v39, v160, v38
	v_cvt_pk_bf16_f32 v214, v6, v38
	v_fma_f32 v7, -v161, v38, v7
	v_fmac_f32_e32 v39, v161, v6
	v_fmac_f32_e32 v20, v160, v7
	v_fmac_f32_e32 v200, v160, v39
	v_cvt_pk_bf16_f32 v215, v7, v39
	v_fma_f32 v20, -v161, v39, v20
	v_fmac_f32_e32 v200, v161, v7
	ds_write2_b32 v224, v214, v215 offset0:136 offset1:204
	v_fmac_f32_e32 v21, v160, v20
	v_fmac_f32_e32 v201, v160, v200
	v_cvt_pk_bf16_f32 v212, v20, v200
	v_fma_f32 v21, -v161, v200, v21
	v_fmac_f32_e32 v201, v161, v20
	v_fmac_f32_e32 v22, v160, v21
	v_fmac_f32_e32 v202, v160, v201
	v_cvt_pk_bf16_f32 v213, v21, v201
	v_fma_f32 v22, -v161, v201, v22
	v_fmac_f32_e32 v202, v161, v21
	ds_write2_b32 v225, v212, v213 offset0:0 offset1:68
	v_fmac_f32_e32 v23, v160, v22
	v_fmac_f32_e32 v203, v160, v202
	v_cvt_pk_bf16_f32 v214, v22, v202
	v_fma_f32 v23, -v161, v202, v23
	v_fmac_f32_e32 v203, v161, v22
	v_fmac_f32_e32 v8, v160, v23
	v_fmac_f32_e32 v40, v160, v203
	v_cvt_pk_bf16_f32 v215, v23, v203
	v_fma_f32 v8, -v161, v203, v8
	v_fmac_f32_e32 v40, v161, v23
	ds_write2_b32 v225, v214, v215 offset0:136 offset1:204
	v_fmac_f32_e32 v9, v160, v8
	v_fmac_f32_e32 v41, v160, v40
	v_cvt_pk_bf16_f32 v212, v8, v40
	v_fma_f32 v9, -v161, v40, v9
	v_fmac_f32_e32 v41, v161, v8
	v_fmac_f32_e32 v10, v160, v9
	v_fmac_f32_e32 v42, v160, v41
	v_cvt_pk_bf16_f32 v213, v9, v41
	v_fma_f32 v10, -v161, v41, v10
	v_fmac_f32_e32 v42, v161, v9
	ds_write2_b32 v226, v212, v213 offset0:0 offset1:68
	v_fmac_f32_e32 v11, v160, v10
	v_fmac_f32_e32 v43, v160, v42
	v_cvt_pk_bf16_f32 v214, v10, v42
	v_fma_f32 v11, -v161, v42, v11
	v_fmac_f32_e32 v43, v161, v10
	v_fmac_f32_e32 v24, v160, v11
	v_fmac_f32_e32 v204, v160, v43
	v_cvt_pk_bf16_f32 v215, v11, v43
	v_fma_f32 v24, -v161, v43, v24
	v_fmac_f32_e32 v204, v161, v11
	ds_write2_b32 v226, v214, v215 offset0:136 offset1:204
	v_fmac_f32_e32 v25, v160, v24
	v_fmac_f32_e32 v205, v160, v204
	v_cvt_pk_bf16_f32 v212, v24, v204
	v_fma_f32 v25, -v161, v204, v25
	v_fmac_f32_e32 v205, v161, v24
	v_fmac_f32_e32 v26, v160, v25
	v_fmac_f32_e32 v206, v160, v205
	v_cvt_pk_bf16_f32 v213, v25, v205
	v_fma_f32 v26, -v161, v205, v26
	v_fmac_f32_e32 v206, v161, v25
	ds_write2_b32 v227, v212, v213 offset0:0 offset1:68
	v_fmac_f32_e32 v27, v160, v26
	v_fmac_f32_e32 v207, v160, v206
	v_cvt_pk_bf16_f32 v214, v26, v206
	v_fma_f32 v27, -v161, v206, v27
	v_fmac_f32_e32 v207, v161, v26
	v_fmac_f32_e32 v12, v160, v27
	v_fmac_f32_e32 v44, v160, v207
	v_cvt_pk_bf16_f32 v215, v27, v207
	v_fma_f32 v12, -v161, v207, v12
	v_fmac_f32_e32 v44, v161, v27
	ds_write2_b32 v227, v214, v215 offset0:136 offset1:204
	v_fmac_f32_e32 v13, v160, v12
	v_fmac_f32_e32 v45, v160, v44
	v_cvt_pk_bf16_f32 v212, v12, v44
	v_fma_f32 v13, -v161, v44, v13
	v_fmac_f32_e32 v45, v161, v12
	v_fmac_f32_e32 v14, v160, v13
	v_fmac_f32_e32 v46, v160, v45
	v_cvt_pk_bf16_f32 v213, v13, v45
	v_fma_f32 v14, -v161, v45, v14
	v_fmac_f32_e32 v46, v161, v13
	ds_write2_b32 v190, v212, v213 offset0:0 offset1:68
	v_fmac_f32_e32 v15, v160, v14
	v_fmac_f32_e32 v47, v160, v46
	v_cvt_pk_bf16_f32 v214, v14, v46
	v_fma_f32 v15, -v161, v46, v15
	v_fmac_f32_e32 v47, v161, v14
	v_fmac_f32_e32 v28, v160, v15
	v_fmac_f32_e32 v208, v160, v47
	v_cvt_pk_bf16_f32 v215, v15, v47
	v_fma_f32 v28, -v161, v47, v28
	v_fmac_f32_e32 v208, v161, v15
	ds_write2_b32 v190, v214, v215 offset0:136 offset1:204
	v_fmac_f32_e32 v29, v160, v28
	v_fmac_f32_e32 v209, v160, v208
	v_cvt_pk_bf16_f32 v212, v28, v208
	v_fma_f32 v29, -v161, v208, v29
	v_fmac_f32_e32 v209, v161, v28
	v_fmac_f32_e32 v30, v160, v29
	v_fmac_f32_e32 v210, v160, v209
	v_cvt_pk_bf16_f32 v213, v29, v209
	v_fma_f32 v30, -v161, v209, v30
	v_fmac_f32_e32 v210, v161, v29
	ds_write2_b32 v191, v212, v213 offset0:0 offset1:68
	v_fmac_f32_e32 v31, v160, v30
	v_fmac_f32_e32 v211, v160, v210
	v_cvt_pk_bf16_f32 v214, v30, v210
	v_fma_f32 v31, -v161, v210, v31
	v_fmac_f32_e32 v211, v161, v30
	v_mov_b32_e32 v188, v31
	v_mov_b32_e32 v189, v211
	v_cvt_pk_bf16_f32 v215, v31, v211
	ds_write2_b32 v191, v214, v215 offset0:136 offset1:204
	s_waitcnt lgkmcnt(0)
	ds_read_b128 v[32:35], v186 offset:18432
	ds_read_b128 v[36:39], v186 offset:18464
	ds_read_b128 v[40:43], v186 offset:18496
	ds_read_b128 v[44:47], v186 offset:18528
	ds_read_b128 v[196:199], v186 offset:18560
	ds_read_b128 v[200:203], v186 offset:18592
	ds_read_b128 v[204:207], v186 offset:18624
	ds_read_b128 v[208:211], v186 offset:18656
	s_waitcnt lgkmcnt(7)
	v_mfma_f32_32x32x16_bf16 v[234:249], v[64:67], v[32:35], 0
	v_fmac_f32_e32 v48, v100, v228
	v_fmac_f32_e32 v49, v101, v229
	v_fmac_f32_e32 v50, v102, v230
	v_fmac_f32_e32 v51, v103, v231
	v_fmac_f32_e32 v52, v80, v232
	v_fmac_f32_e32 v53, v81, v233
	v_fmac_f32_e32 v54, v82, v251
	v_fmac_f32_e32 v55, v83, v252
	v_mul_f32_e32 v56, v48, v48
	s_waitcnt lgkmcnt(6)
	v_mfma_f32_32x32x16_bf16 v[234:249], v[68:71], v[36:39], v[234:249]
	v_mul_f32_e32 v57, v49, v49
	v_mul_f32_e32 v58, v50, v50
	v_mul_f32_e32 v59, v51, v51
	v_mul_f32_e32 v60, v52, v52
	v_mul_f32_e32 v61, v53, v53
	v_mul_f32_e32 v62, v54, v54
	v_mul_f32_e32 v63, v55, v55
	v_fmaak_f32 v56, v56, v184, 0xc0135761
	v_fmaak_f32 v57, v57, v184, 0xc0135761
	s_waitcnt lgkmcnt(5)
	v_mfma_f32_32x32x16_bf16 v[234:249], v[72:75], v[40:43], v[234:249]
	v_fmaak_f32 v58, v58, v184, 0xc0135761
	v_fmaak_f32 v59, v59, v184, 0xc0135761
	v_fmaak_f32 v60, v60, v184, 0xc0135761
	v_fmaak_f32 v61, v61, v184, 0xc0135761
	v_fmaak_f32 v62, v62, v184, 0xc0135761
	v_fmaak_f32 v63, v63, v184, 0xc0135761
	v_mul_f32_e32 v56, v48, v56
	v_mul_f32_e32 v57, v49, v57
	v_mul_f32_e32 v58, v50, v58
	s_waitcnt lgkmcnt(4)
	v_mfma_f32_32x32x16_bf16 v[234:249], v[76:79], v[44:47], v[234:249]
	v_mul_f32_e32 v59, v51, v59
	v_mul_f32_e32 v60, v52, v60
	v_mul_f32_e32 v61, v53, v61
	v_mul_f32_e32 v62, v54, v62
	v_mul_f32_e32 v63, v55, v63
	v_exp_f32_e32 v56, v56
	v_exp_f32_e32 v57, v57
	v_exp_f32_e32 v58, v58
	v_exp_f32_e32 v59, v59
	s_waitcnt lgkmcnt(3)
	v_mfma_f32_32x32x16_bf16 v[234:249], v[84:87], v[196:199], v[234:249]
	v_exp_f32_e32 v60, v60
	v_exp_f32_e32 v61, v61
	v_exp_f32_e32 v62, v62
	v_exp_f32_e32 v63, v63
	v_add_f32_e32 v56, 1.0, v56
	v_add_f32_e32 v57, 1.0, v57
	v_add_f32_e32 v58, 1.0, v58
	v_add_f32_e32 v59, 1.0, v59
	s_waitcnt lgkmcnt(2)
	v_mfma_f32_32x32x16_bf16 v[234:249], v[88:91], v[200:203], v[234:249]
	v_add_f32_e32 v60, 1.0, v60
	v_add_f32_e32 v61, 1.0, v61
	v_add_f32_e32 v62, 1.0, v62
	v_add_f32_e32 v63, 1.0, v63
	v_rcp_f32_e32 v56, v56
	v_rcp_f32_e32 v57, v57
	v_rcp_f32_e32 v58, v58
	v_rcp_f32_e32 v59, v59
	s_waitcnt lgkmcnt(1)
	v_mfma_f32_32x32x16_bf16 v[234:249], v[96:99], v[204:207], v[234:249]
	v_rcp_f32_e32 v60, v60
	v_rcp_f32_e32 v61, v61
	v_rcp_f32_e32 v62, v62
	v_rcp_f32_e32 v63, v63
	v_mul_f32_e32 v48, v48, v56
	v_mul_f32_e32 v49, v49, v57
	v_mul_f32_e32 v50, v50, v58
	v_mul_f32_e32 v51, v51, v59
	s_waitcnt lgkmcnt(0)
	v_mfma_f32_32x32x16_bf16 v[234:249], v[108:111], v[208:211], v[234:249]
	v_mul_f32_e32 v52, v52, v60
	v_mul_f32_e32 v53, v53, v61
	v_mul_f32_e32 v54, v54, v62
	v_mul_f32_e32 v55, v55, v63
	v_cvt_pk_bf16_f32 v56, v48, v49
	v_cvt_pk_bf16_f32 v57, v50, v51
	v_cvt_pk_bf16_f32 v58, v52, v53
	v_cvt_pk_bf16_f32 v59, v54, v55
	global_store_dwordx2 v253, v[56:57], s[14:15]
	global_store_dwordx2 v254, v[58:59], s[14:15]
	s_movk_i32 s18, 0x1000
	s_and_b32 s17, s16, 0x3800
	s_cmp_eq_u32 s17, 0x800
	s_cselect_b32 s18, 0x1f9000, s18
	s_add_u32 s14, s14, s18
	s_addc_u32 s15, s15, 0
	s_cmp_eq_u32 s0, 0x1080000
	s_cbranch_scc0 .Lscan_tile
	s_nop 11
	v_fmac_f32_e32 v234, v100, v162
	v_fmac_f32_e32 v235, v101, v163
	v_fmac_f32_e32 v236, v102, v164
	v_fmac_f32_e32 v237, v103, v165
	v_fmac_f32_e32 v238, v80, v166
	v_fmac_f32_e32 v239, v81, v167
	v_fmac_f32_e32 v240, v82, v192
	v_fmac_f32_e32 v241, v83, v193
	v_mul_f32_e32 v242, v234, v234
	v_mul_f32_e32 v243, v235, v235
	v_mul_f32_e32 v244, v236, v236
	v_mul_f32_e32 v245, v237, v237
	v_mul_f32_e32 v246, v238, v238
	v_mul_f32_e32 v247, v239, v239
	v_mul_f32_e32 v248, v240, v240
	v_mul_f32_e32 v249, v241, v241
	v_fmaak_f32 v242, v242, v184, 0xc0135761
	v_fmaak_f32 v243, v243, v184, 0xc0135761
	v_fmaak_f32 v244, v244, v184, 0xc0135761
	v_fmaak_f32 v245, v245, v184, 0xc0135761
	v_fmaak_f32 v246, v246, v184, 0xc0135761
	v_fmaak_f32 v247, v247, v184, 0xc0135761
	v_fmaak_f32 v248, v248, v184, 0xc0135761
	v_fmaak_f32 v249, v249, v184, 0xc0135761
	v_mul_f32_e32 v242, v234, v242
	v_mul_f32_e32 v243, v235, v243
	v_mul_f32_e32 v244, v236, v244
	v_mul_f32_e32 v245, v237, v245
	v_mul_f32_e32 v246, v238, v246
	v_mul_f32_e32 v247, v239, v247
	v_mul_f32_e32 v248, v240, v248
	v_mul_f32_e32 v249, v241, v249
	v_exp_f32_e32 v242, v242
	v_exp_f32_e32 v243, v243
	v_exp_f32_e32 v244, v244
	v_exp_f32_e32 v245, v245
	v_exp_f32_e32 v246, v246
	v_exp_f32_e32 v247, v247
	v_exp_f32_e32 v248, v248
	v_exp_f32_e32 v249, v249
	v_add_f32_e32 v242, 1.0, v242
	v_add_f32_e32 v243, 1.0, v243
	v_add_f32_e32 v244, 1.0, v244
	v_add_f32_e32 v245, 1.0, v245
	v_add_f32_e32 v246, 1.0, v246
	v_add_f32_e32 v247, 1.0, v247
	v_add_f32_e32 v248, 1.0, v248
	v_add_f32_e32 v249, 1.0, v249
	v_rcp_f32_e32 v242, v242
	v_rcp_f32_e32 v243, v243
	v_rcp_f32_e32 v244, v244
	v_rcp_f32_e32 v245, v245
	v_rcp_f32_e32 v246, v246
	v_rcp_f32_e32 v247, v247
	v_rcp_f32_e32 v248, v248
	v_rcp_f32_e32 v249, v249
	v_mul_f32_e32 v234, v234, v242
	v_mul_f32_e32 v235, v235, v243
	v_mul_f32_e32 v236, v236, v244
	v_mul_f32_e32 v237, v237, v245
	v_mul_f32_e32 v238, v238, v246
	v_mul_f32_e32 v239, v239, v247
	v_mul_f32_e32 v240, v240, v248
	v_mul_f32_e32 v241, v241, v249
	v_cvt_pk_bf16_f32 v242, v234, v235
	v_cvt_pk_bf16_f32 v243, v236, v237
	v_cvt_pk_bf16_f32 v244, v238, v239
	v_cvt_pk_bf16_f32 v245, v240, v241
	global_store_dwordx2 v253, v[242:243], s[14:15]
	global_store_dwordx2 v254, v[244:245], s[14:15]
	s_add_i32 s6, s6, s7
	s_add_i32 s10, s10, s11
	s_add_i32 s12, s12, s7
	s_cmpk_gt_i32 s6, 0x3ff
	s_cbranch_scc0 .LBB0_563
